# nt hint on the final RMSNorm phase output stores
# speedup vs baseline: 1.0186x; 1.0113x over previous
.LBB0_19:
	s_load_dwordx2 s[6:7], s[0:1], 0x98
	s_waitcnt lgkmcnt(0)
	s_add_u32 s6, s6, s26
	s_addc_u32 s7, s7, s27
	global_load_dwordx4 v[0:3], v97, s[6:7] offset:-48
	s_load_dwordx2 s[6:7], s[0:1], 0x98
	s_waitcnt lgkmcnt(0)
	v_lshl_add_u64 v[4:5], s[6:7], 0, v[10:11]
	global_load_dwordx2 v[16:17], v[4:5], off offset:-1536
	s_load_dwordx2 s[6:7], s[0:1], 0x98
	s_waitcnt lgkmcnt(0)
	v_lshl_add_u64 v[4:5], s[6:7], 0, v[10:11]
	global_load_dwordx2 v[14:15], v[4:5], off offset:-1024
	s_load_dwordx2 s[6:7], s[0:1], 0x98
	s_waitcnt lgkmcnt(0)
	v_lshl_add_u64 v[4:5], s[6:7], 0, v[10:11]
	global_load_dwordx2 v[12:13], v[4:5], off offset:-512
	s_load_dwordx2 s[6:7], s[0:1], 0x98
	s_waitcnt lgkmcnt(0)
	v_lshl_add_u64 v[4:5], s[6:7], 0, v[10:11]
	global_load_dwordx2 v[26:27], v[4:5], off
	s_load_dwordx2 s[6:7], s[0:1], 0x98
	v_subrev_co_u32_e32 v10, vcc, s18, v10
	s_waitcnt lgkmcnt(0)
	s_add_u32 s6, s6, s26
	s_addc_u32 s7, s7, s27
	global_load_dwordx4 v[22:25], v97, s[6:7] offset:-32
	s_load_dwordx2 s[6:7], s[0:1], 0x98
	s_add_i32 s22, s12, -2
	s_ashr_i32 s23, s22, 31
	s_lshl_b64 s[8:9], s[22:23], 11
	v_subb_co_u32_e32 v11, vcc, v11, v52, vcc
	s_waitcnt lgkmcnt(0)
	s_add_u32 s6, s6, s8
	s_addc_u32 s7, s7, s9
	v_lshl_add_u64 v[4:5], s[6:7], 0, v[96:97]
	v_add_co_u32_e32 v4, vcc, s51, v4
	s_waitcnt vmcnt(5)
	v_mov_b32_e32 v30, v1
	v_addc_co_u32_e32 v5, vcc, 0, v5, vcc
	global_load_dwordx2 v[28:29], v[4:5], off
	s_load_dwordx2 s[6:7], s[0:1], 0x98
	v_mov_b32_e32 v31, v2
	v_mov_b32_e32 v1, v3
	v_pk_add_f32 v[0:1], v[30:31], v[0:1]
	s_waitcnt vmcnt(5)
	v_lshlrev_b32_e32 v32, 16, v16
	s_waitcnt lgkmcnt(0)
	s_add_u32 s6, s6, s8
	s_addc_u32 s7, s7, s9
	v_lshl_add_u64 v[4:5], s[6:7], 0, v[96:97]
	v_add_co_u32_e32 v4, vcc, s51, v4
	v_and_b32_e32 v33, 0xffff0000, v16
	s_nop 0
	v_addc_co_u32_e32 v5, vcc, 0, v5, vcc
	global_load_dwordx2 v[44:45], v[4:5], off offset:512
	s_load_dwordx2 s[6:7], s[0:1], 0x98
	v_lshlrev_b32_e32 v36, 16, v17
	v_and_b32_e32 v37, 0xffff0000, v17
	s_waitcnt vmcnt(5)
	v_lshlrev_b32_e32 v40, 16, v14
	v_and_b32_e32 v41, 0xffff0000, v14
	s_waitcnt lgkmcnt(0)
	s_add_u32 s6, s6, s8
	s_addc_u32 s7, s7, s9
	v_lshl_add_u64 v[4:5], s[6:7], 0, v[96:97]
	v_add_co_u32_e32 v4, vcc, s51, v4
	s_waitcnt vmcnt(4)
	v_lshlrev_b32_e32 v42, 16, v12
	v_addc_co_u32_e32 v5, vcc, 0, v5, vcc
	global_load_dwordx2 v[20:21], v[4:5], off offset:1024
	s_load_dwordx2 s[6:7], s[0:1], 0x98
	v_and_b32_e32 v43, 0xffff0000, v12
	v_lshlrev_b32_e32 v46, 16, v13
	v_and_b32_e32 v47, 0xffff0000, v13
	s_waitcnt vmcnt(4)
	v_lshlrev_b32_e32 v48, 16, v26
	s_waitcnt lgkmcnt(0)
	s_add_u32 s6, s6, s8
	s_addc_u32 s7, s7, s9
	v_lshl_add_u64 v[4:5], s[6:7], 0, v[96:97]
	v_add_co_u32_e32 v4, vcc, s51, v4
	v_and_b32_e32 v49, 0xffff0000, v26
	s_nop 0
	v_addc_co_u32_e32 v5, vcc, 0, v5, vcc
	global_load_dwordx2 v[18:19], v[4:5], off offset:1536
	s_load_dwordx2 s[6:7], s[0:1], 0x98
	v_lshlrev_b32_e32 v54, 16, v27
	v_and_b32_e32 v55, 0xffff0000, v27
	s_waitcnt vmcnt(4)
	v_mov_b32_e32 v26, v23
	v_mov_b32_e32 v27, v24
	s_waitcnt lgkmcnt(0)
	s_add_u32 s6, s6, s26
	s_addc_u32 s7, s7, s27
	global_load_dwordx4 v[4:7], v97, s[6:7] offset:-16
	s_load_dwordx2 s[8:9], s[0:1], 0x98
	s_add_i32 s20, s12, -1
	s_ashr_i32 s21, s20, 31
	s_lshl_b64 s[6:7], s[20:21], 11
	v_mov_b32_e32 v23, v25
	s_waitcnt lgkmcnt(0)
	s_add_u32 s8, s8, s6
	s_addc_u32 s9, s9, s7
	v_lshl_add_u64 v[30:31], s[8:9], 0, v[96:97]
	v_add_co_u32_e32 v30, vcc, s51, v30
	v_pk_add_f32 v[22:23], v[26:27], v[22:23]
	s_nop 0
	v_addc_co_u32_e32 v31, vcc, 0, v31, vcc
	global_load_dwordx2 v[16:17], v[30:31], off
	s_load_dwordx2 s[8:9], s[0:1], 0x98
	v_lshlrev_b32_e32 v30, 16, v15
	v_and_b32_e32 v31, 0xffff0000, v15
	v_mov_b32_e32 v3, v0
	v_mov_b32_e32 v2, v22
	s_waitcnt lgkmcnt(0)
	s_add_u32 s8, s8, s6
	s_addc_u32 s9, s9, s7
	v_lshl_add_u64 v[14:15], s[8:9], 0, v[96:97]
	v_add_co_u32_e32 v14, vcc, s51, v14
	v_mov_b32_e32 v0, v23
	s_nop 0
	v_addc_co_u32_e32 v15, vcc, 0, v15, vcc
	global_load_dwordx2 v[14:15], v[14:15], off offset:512
	s_load_dwordx2 s[8:9], s[0:1], 0x98
	v_pk_add_f32 v[0:1], v[2:3], v[0:1]
	s_waitcnt lgkmcnt(0)
	s_add_u32 s8, s8, s6
	s_addc_u32 s9, s9, s7
	v_lshl_add_u64 v[12:13], s[8:9], 0, v[96:97]
	v_add_co_u32_e32 v12, vcc, s51, v12
	v_pk_fma_f32 v[0:1], v[0:1], s[30:31], v[172:173] op_sel_hi:[1,0,0]
	s_nop 0
	v_addc_co_u32_e32 v13, vcc, 0, v13, vcc
	global_load_dwordx2 v[12:13], v[12:13], off offset:1024
	s_load_dwordx2 s[8:9], s[0:1], 0x98
	v_mul_f32_e32 v22, 0x4b800000, v1
	v_mul_f32_e32 v23, 0x4b800000, v0
	s_waitcnt lgkmcnt(0)
	s_add_u32 s6, s8, s6
	s_addc_u32 s7, s9, s7
	v_lshl_add_u64 v[2:3], s[6:7], 0, v[96:97]
	v_add_co_u32_e32 v2, vcc, s51, v2
	v_cmp_gt_f32_e64 s[6:7], s59, v0
	v_cmp_gt_f32_e64 s[8:9], s59, v1
	v_addc_co_u32_e32 v3, vcc, 0, v3, vcc
	s_nop 0
	v_cndmask_b32_e64 v1, v1, v22, s[8:9]
	v_cndmask_b32_e64 v0, v0, v23, s[6:7]
	global_load_dwordx2 v[34:35], v[2:3], off offset:1536
	s_load_dwordx2 s[28:29], s[0:1], 0x98
	v_rsq_f32_e32 v22, v1
	v_rsq_f32_e32 v23, v0
	s_waitcnt vmcnt(8)
	v_lshlrev_b32_e32 v0, 16, v28
	v_and_b32_e32 v1, 0xffff0000, v28
	v_mul_f32_e32 v24, 0x45800000, v22
	v_mul_f32_e32 v25, 0x45800000, v23
	s_waitcnt lgkmcnt(0)
	s_add_u32 s28, s28, s26
	v_lshlrev_b32_e32 v2, 16, v29
	v_and_b32_e32 v3, 0xffff0000, v29
	v_cndmask_b32_e64 v24, v22, v24, s[8:9]
	v_cndmask_b32_e64 v56, v23, v25, s[6:7]
	s_addc_u32 s29, s29, s27
	v_pk_mul_f32 v[38:39], v[24:25], v[32:33] op_sel_hi:[0,1]
	v_pk_mul_f32 v[32:33], v[24:25], v[40:41] op_sel_hi:[0,1]
	v_pk_mul_f32 v[28:29], v[24:25], v[42:43] op_sel_hi:[0,1]
	v_pk_mul_f32 v[40:41], v[56:57], v[2:3] op_sel_hi:[0,1]
	v_pk_mul_f32 v[42:43], v[56:57], v[0:1] op_sel_hi:[0,1]
	global_load_dwordx4 v[0:3], v97, s[28:29]
	s_load_dwordx2 s[8:9], s[0:1], 0x98
	s_ashr_i32 s13, s12, 31
	s_lshl_b64 s[6:7], s[12:13], 11
	v_pk_mul_f32 v[36:37], v[24:25], v[36:37] op_sel_hi:[0,1]
	v_pk_mul_f32 v[30:31], v[24:25], v[30:31] op_sel_hi:[0,1]
	s_waitcnt lgkmcnt(0)
	s_add_u32 s8, s8, s6
	s_addc_u32 s9, s9, s7
	v_pk_mul_f32 v[26:27], v[24:25], v[46:47] op_sel_hi:[0,1]
	v_pk_mul_f32 v[22:23], v[24:25], v[54:55] op_sel_hi:[0,1]
	v_pk_mul_f32 v[24:25], v[24:25], v[48:49] op_sel_hi:[0,1]
	v_lshl_add_u64 v[48:49], s[8:9], 0, v[96:97]
	v_add_co_u32_e32 v48, vcc, s51, v48
	s_waitcnt vmcnt(8)
	v_lshlrev_b32_e32 v46, 16, v44
	v_addc_co_u32_e32 v49, vcc, 0, v49, vcc
	global_load_dwordx2 v[62:63], v[48:49], off
	s_load_dwordx2 s[8:9], s[0:1], 0x98
	s_waitcnt vmcnt(5)
	v_lshlrev_b32_e32 v78, 16, v16
	v_and_b32_e32 v79, 0xffff0000, v16
	v_lshlrev_b32_e32 v80, 16, v17
	v_and_b32_e32 v81, 0xffff0000, v17
	s_waitcnt lgkmcnt(0)
	s_add_u32 s8, s8, s6
	s_addc_u32 s9, s9, s7
	v_lshl_add_u64 v[54:55], s[8:9], 0, v[96:97]
	v_add_co_u32_e32 v54, vcc, s51, v54
	v_and_b32_e32 v47, 0xffff0000, v44
	s_nop 0
	v_addc_co_u32_e32 v55, vcc, 0, v55, vcc
	global_load_dwordx2 v[64:65], v[54:55], off offset:512
	s_load_dwordx2 s[8:9], s[0:1], 0x98
	v_lshlrev_b32_e32 v54, 16, v18
	v_and_b32_e32 v55, 0xffff0000, v18
	v_lshlrev_b32_e32 v18, 16, v19
	v_and_b32_e32 v19, 0xffff0000, v19
	s_waitcnt lgkmcnt(0)
	s_add_u32 s8, s8, s6
	s_addc_u32 s9, s9, s7
	v_lshl_add_u64 v[58:59], s[8:9], 0, v[96:97]
	v_pk_mul_f32 v[66:67], v[56:57], v[18:19] op_sel_hi:[0,1]
	v_add_co_u32_e32 v18, vcc, s51, v58
	v_lshlrev_b32_e32 v44, 16, v45
	s_nop 0
	v_addc_co_u32_e32 v19, vcc, 0, v59, vcc
	global_load_dwordx2 v[70:71], v[18:19], off offset:1024
	s_load_dwordx2 s[8:9], s[0:1], 0x98
	v_mov_b32_e32 v18, v5
	v_mov_b32_e32 v19, v6
	v_mov_b32_e32 v5, v7
	v_pk_add_f32 v[72:73], v[18:19], v[4:5]
	s_waitcnt lgkmcnt(0)
	s_add_u32 s6, s8, s6
	s_addc_u32 s7, s9, s7
	v_lshl_add_u64 v[4:5], s[6:7], 0, v[96:97]
	v_add_co_u32_e32 v4, vcc, s51, v4
	v_and_b32_e32 v45, 0xffff0000, v45
	s_nop 0
	v_addc_co_u32_e32 v5, vcc, 0, v5, vcc
	global_load_dwordx2 v[76:77], v[4:5], off offset:1536
	s_load_dwordx2 s[6:7], s[0:1], 0x88
	v_lshlrev_b32_e32 v48, 16, v20
	v_and_b32_e32 v49, 0xffff0000, v20
	v_lshlrev_b32_e32 v20, 16, v21
	v_and_b32_e32 v21, 0xffff0000, v21
	s_waitcnt lgkmcnt(0)
	global_load_dwordx4 v[4:7], v50, s[6:7]
	s_load_dwordx2 s[6:7], s[0:1], 0x88
	v_pk_mul_f32 v[44:45], v[56:57], v[44:45] op_sel_hi:[0,1]
	v_pk_mul_f32 v[46:47], v[56:57], v[46:47] op_sel_hi:[0,1]
	v_pk_mul_f32 v[20:21], v[56:57], v[20:21] op_sel_hi:[0,1]
	v_pk_mul_f32 v[48:49], v[56:57], v[48:49] op_sel_hi:[0,1]
	s_waitcnt lgkmcnt(0)
	global_load_dwordx4 v[16:19], v50, s[6:7] offset:1024
	s_load_dwordx2 s[6:7], s[0:1], 0x88
	v_pk_mul_f32 v[68:69], v[56:57], v[54:55] op_sel_hi:[0,1]
	v_mov_b32_e32 v75, v72
	s_waitcnt vmcnt(9)
	v_lshlrev_b32_e32 v82, 16, v14
	v_and_b32_e32 v83, 0xffff0000, v14
	s_waitcnt lgkmcnt(0)
	global_load_dwordx4 v[54:57], v50, s[6:7] offset:2048
	s_load_dwordx2 s[6:7], s[0:1], 0x88
	s_waitcnt vmcnt(7)
	v_mov_b32_e32 v90, v1
	v_mov_b32_e32 v91, v2
	v_mov_b32_e32 v1, v3
	v_pk_add_f32 v[0:1], v[90:91], v[0:1]
	s_waitcnt lgkmcnt(0)
	global_load_dwordx4 v[58:61], v50, s[6:7] offset:3072
	s_load_dwordx2 s[6:7], s[0:1], 0x90
	v_mov_b32_e32 v74, v0
	v_mov_b32_e32 v72, v1
	v_pk_add_f32 v[0:1], v[74:75], v[72:73]
	v_lshlrev_b32_e32 v14, 16, v15
	v_pk_fma_f32 v[0:1], v[0:1], s[30:31], v[172:173] op_sel_hi:[1,0,0]
	s_waitcnt lgkmcnt(0)
	v_lshl_add_u64 v[86:87], s[6:7], 0, v[8:9]
	v_mul_f32_e32 v2, 0x4b800000, v1
	v_mul_f32_e32 v3, 0x4b800000, v0
	v_cmp_gt_f32_e32 vcc, s59, v0
	v_cmp_gt_f32_e64 s[6:7], s59, v1
	v_and_b32_e32 v15, 0xffff0000, v15
	v_cndmask_b32_e32 v0, v0, v3, vcc
	v_cndmask_b32_e64 v1, v1, v2, s[6:7]
	v_rsq_f32_e32 v53, v1
	v_rsq_f32_e32 v72, v0
	s_waitcnt vmcnt(7)
	v_lshlrev_b32_e32 v0, 16, v62
	v_and_b32_e32 v1, 0xffff0000, v62
	v_lshlrev_b32_e32 v2, 16, v63
	v_and_b32_e32 v3, 0xffff0000, v63
	v_mul_f32_e32 v62, 0x45800000, v53
	v_mul_f32_e32 v63, 0x45800000, v72
	v_lshlrev_b32_e32 v84, 16, v12
	v_and_b32_e32 v85, 0xffff0000, v12
	v_lshlrev_b32_e32 v12, 16, v13
	v_and_b32_e32 v13, 0xffff0000, v13
	v_lshlrev_b32_e32 v88, 16, v34
	v_and_b32_e32 v89, 0xffff0000, v34
	v_lshlrev_b32_e32 v34, 16, v35
	v_and_b32_e32 v35, 0xffff0000, v35
	v_cndmask_b32_e64 v62, v53, v62, s[6:7]
	v_cndmask_b32_e32 v72, v72, v63, vcc
	v_pk_mul_f32 v[74:75], v[62:63], v[80:81] op_sel_hi:[0,1]
	v_pk_mul_f32 v[78:79], v[62:63], v[78:79] op_sel_hi:[0,1]
	v_pk_mul_f32 v[80:81], v[62:63], v[14:15] op_sel_hi:[0,1]
	v_pk_mul_f32 v[82:83], v[62:63], v[82:83] op_sel_hi:[0,1]
	v_pk_mul_f32 v[90:91], v[62:63], v[12:13] op_sel_hi:[0,1]
	v_pk_mul_f32 v[84:85], v[62:63], v[84:85] op_sel_hi:[0,1]
	v_pk_mul_f32 v[92:93], v[62:63], v[34:35] op_sel_hi:[0,1]
	v_pk_mul_f32 v[62:63], v[62:63], v[88:89] op_sel_hi:[0,1]
	v_pk_mul_f32 v[88:89], v[72:73], v[2:3] op_sel_hi:[0,1]
	v_pk_mul_f32 v[94:95], v[72:73], v[0:1] op_sel_hi:[0,1]
	s_waitcnt vmcnt(6)
	v_lshlrev_b32_e32 v0, 16, v64
	v_and_b32_e32 v1, 0xffff0000, v64
	v_lshlrev_b32_e32 v2, 16, v65
	v_and_b32_e32 v3, 0xffff0000, v65
	v_pk_mul_f32 v[64:65], v[72:73], v[2:3] op_sel_hi:[0,1]
	v_pk_mul_f32 v[98:99], v[72:73], v[0:1] op_sel_hi:[0,1]
	s_waitcnt vmcnt(5)
	v_lshlrev_b32_e32 v0, 16, v70
	v_and_b32_e32 v1, 0xffff0000, v70
	v_lshlrev_b32_e32 v2, 16, v71
	v_and_b32_e32 v3, 0xffff0000, v71
	v_pk_mul_f32 v[70:71], v[72:73], v[2:3] op_sel_hi:[0,1]
	v_pk_mul_f32 v[100:101], v[72:73], v[0:1] op_sel_hi:[0,1]
	s_lshl_b64 s[8:9], s[22:23], 12
	s_waitcnt vmcnt(4)
	v_lshlrev_b32_e32 v0, 16, v76
	v_and_b32_e32 v1, 0xffff0000, v76
	v_lshlrev_b32_e32 v2, 16, v77
	v_and_b32_e32 v3, 0xffff0000, v77
	v_pk_mul_f32 v[76:77], v[72:73], v[2:3] op_sel_hi:[0,1]
	v_pk_mul_f32 v[72:73], v[72:73], v[0:1] op_sel_hi:[0,1]
	s_waitcnt vmcnt(3)
	v_pk_mul_f32 v[0:1], v[4:5], v[38:39]
	v_pk_mul_f32 v[2:3], v[6:7], v[36:37]
	global_store_dwordx4 v[86:87], v[0:3], off offset:-3072 nt
	s_load_dwordx2 s[6:7], s[0:1], 0x90
	v_pk_mul_f32 v[12:13], v[4:5], v[42:43]
	v_pk_mul_f32 v[14:15], v[6:7], v[40:41]
	s_waitcnt vmcnt(3)
	v_pk_mul_f32 v[0:1], v[16:17], v[32:33]
	v_pk_mul_f32 v[2:3], v[18:19], v[30:31]
	s_waitcnt lgkmcnt(0)
	v_lshl_add_u64 v[30:31], s[6:7], 0, v[8:9]
	global_store_dwordx4 v[30:31], v[0:3], off offset:-2048 nt
	s_load_dwordx2 s[6:7], s[0:1], 0x90
	v_pk_mul_f32 v[34:35], v[4:5], v[78:79]
	s_waitcnt vmcnt(3)
	v_pk_mul_f32 v[0:1], v[54:55], v[28:29]
	v_pk_mul_f32 v[2:3], v[56:57], v[26:27]
	v_pk_mul_f32 v[36:37], v[6:7], v[74:75]
	s_waitcnt lgkmcnt(0)
	v_lshl_add_u64 v[26:27], s[6:7], 0, v[8:9]
	global_store_dwordx4 v[26:27], v[0:3], off offset:-1024 nt
	s_load_dwordx2 s[6:7], s[0:1], 0x90
	v_pk_mul_f32 v[4:5], v[4:5], v[94:95]
	s_waitcnt vmcnt(3)
	v_pk_mul_f32 v[0:1], v[58:59], v[24:25]
	v_pk_mul_f32 v[2:3], v[60:61], v[22:23]
	v_pk_mul_f32 v[6:7], v[6:7], v[88:89]
	s_waitcnt lgkmcnt(0)
	v_lshl_add_u64 v[22:23], s[6:7], 0, v[8:9]
	global_store_dwordx4 v[22:23], v[0:3], off nt
	s_load_dwordx2 s[6:7], s[0:1], 0x90
	v_subrev_co_u32_e32 v8, vcc, s16, v8
	v_pk_mul_f32 v[0:1], v[16:17], v[46:47]
	v_pk_mul_f32 v[2:3], v[18:19], v[44:45]
	s_waitcnt lgkmcnt(0)
	s_add_u32 s6, s6, s8
	s_addc_u32 s7, s7, s9
	global_store_dwordx4 v50, v[12:15], s[6:7] nt
	s_load_dwordx2 s[6:7], s[0:1], 0x90
	v_subb_co_u32_e32 v9, vcc, v9, v51, vcc
	v_pk_mul_f32 v[12:13], v[16:17], v[82:83]
	v_pk_mul_f32 v[14:15], v[18:19], v[80:81]
	s_waitcnt lgkmcnt(0)
	s_add_u32 s6, s6, s8
	s_addc_u32 s7, s7, s9
	global_store_dwordx4 v50, v[0:3], s[6:7] offset:1024 nt
	s_load_dwordx2 s[6:7], s[0:1], 0x90
	s_waitcnt lgkmcnt(0)
	s_add_u32 s6, s6, s8
	v_pk_mul_f32 v[0:1], v[54:55], v[48:49]
	v_pk_mul_f32 v[2:3], v[56:57], v[20:21]
	s_addc_u32 s7, s7, s9
	global_store_dwordx4 v50, v[0:3], s[6:7] offset:2048 nt
	s_load_dwordx2 s[6:7], s[0:1], 0x90
	s_waitcnt lgkmcnt(0)
	s_add_u32 s6, s6, s8
	v_pk_mul_f32 v[0:1], v[58:59], v[68:69]
	v_pk_mul_f32 v[2:3], v[60:61], v[66:67]
	s_addc_u32 s7, s7, s9
	global_store_dwordx4 v50, v[0:3], s[6:7] offset:3072 nt
	s_load_dwordx2 s[6:7], s[0:1], 0x90
	s_lshl_b64 s[8:9], s[20:21], 12
	v_pk_mul_f32 v[0:1], v[16:17], v[98:99]
	v_pk_mul_f32 v[2:3], v[18:19], v[64:65]
	v_pk_mul_f32 v[16:17], v[54:55], v[84:85]
	s_waitcnt lgkmcnt(0)
	s_add_u32 s6, s6, s8
	s_addc_u32 s7, s7, s9
	global_store_dwordx4 v50, v[34:37], s[6:7] nt
	s_load_dwordx2 s[6:7], s[0:1], 0x90
	v_pk_mul_f32 v[18:19], v[56:57], v[90:91]
	s_waitcnt lgkmcnt(0)
	s_add_u32 s6, s6, s8
	s_addc_u32 s7, s7, s9
	global_store_dwordx4 v50, v[12:15], s[6:7] offset:1024 nt
	s_load_dwordx2 s[6:7], s[0:1], 0x90
	s_waitcnt lgkmcnt(0)
	s_add_u32 s6, s6, s8
	s_addc_u32 s7, s7, s9
	global_store_dwordx4 v50, v[16:19], s[6:7] offset:2048 nt
	s_load_dwordx2 s[6:7], s[0:1], 0x90
	v_pk_mul_f32 v[14:15], v[58:59], v[62:63]
	v_pk_mul_f32 v[16:17], v[60:61], v[92:93]
	v_pk_mul_f32 v[12:13], v[54:55], v[100:101]
	s_waitcnt lgkmcnt(0)
	s_add_u32 s6, s6, s8
	s_addc_u32 s7, s7, s9
	global_store_dwordx4 v50, v[14:17], s[6:7] offset:3072 nt
	s_load_dwordx2 s[6:7], s[0:1], 0x90
	s_lshl_b64 s[8:9], s[12:13], 12
	v_pk_mul_f32 v[14:15], v[56:57], v[70:71]
	s_waitcnt lgkmcnt(0)
	s_add_u32 s6, s6, s8
	s_addc_u32 s7, s7, s9
	global_store_dwordx4 v50, v[4:7], s[6:7] nt
	s_load_dwordx2 s[6:7], s[0:1], 0x90
	s_waitcnt lgkmcnt(0)
	s_add_u32 s6, s6, s8
	s_addc_u32 s7, s7, s9
	global_store_dwordx4 v50, v[0:3], s[6:7] offset:1024 nt
	s_load_dwordx2 s[6:7], s[0:1], 0x90
	v_pk_mul_f32 v[4:5], v[58:59], v[72:73]
	v_pk_mul_f32 v[6:7], v[60:61], v[76:77]
	s_waitcnt lgkmcnt(0)
	s_add_u32 s6, s6, s8
	s_addc_u32 s7, s7, s9
	global_store_dwordx4 v50, v[12:15], s[6:7] offset:2048 nt
	s_load_dwordx2 s[6:7], s[0:1], 0x90
	s_waitcnt lgkmcnt(0)
	s_add_u32 s6, s6, s8
	s_addc_u32 s7, s7, s9
	s_add_i32 s4, s4, s10
	s_sub_i32 s12, s12, s10
	s_sub_u32 s26, s26, s14
	s_subb_u32 s27, s27, s15
	s_cmp_gt_i32 s4, 0x101ff
	global_store_dwordx4 v50, v[4:7], s[6:7] offset:3072 nt
	s_cbranch_scc0 .LBB0_19
